# v10 + transpose tile loops: touch-prefetch of the tile after next (+64 cols) behind the next tile's loads, counted wait vmcnt(3) instead of vmcnt(0)
# speedup vs baseline: 1.0027x; 1.0027x over previous
.LBB0_110:
	s_cmp_eq_u32 s98, 0
	s_cbranch_scc1 .Lpf_first_0
	s_waitcnt vmcnt(3)
	v_mov_b32_e32 v6, v14
	v_mov_b32_e32 v7, v15
	v_mov_b32_e32 v8, v16
	v_mov_b32_e32 v9, v17
	v_mov_b32_e32 v2, v10
	v_mov_b32_e32 v3, v11
	v_mov_b32_e32 v4, v12
	v_mov_b32_e32 v5, v13
	s_branch .Ltsb_skip_0

.Ltsb_skip_0:
	s_mov_b32 s98, 1
	v_add_u32_e32 v10, s22, v18
	v_add_u32_e32 v252, 64, v10
	v_cmp_gt_i32_e32 vcc, s9, v252
	v_cndmask_b32_e64 v252, 0, 1, vcc
	v_lshlrev_b32_e32 v252, 8, v252
	v_mov_b32_e32 v253, 0
	s_lshl_b32 s27, s10, 6
	v_cmp_gt_i32_e32 vcc, s9, v10
	v_mov_b32_e32 v10, 0
	v_mov_b32_e32 v11, 0
	v_mov_b32_e32 v12, 0
	v_mov_b32_e32 v13, 0
	v_mov_b32_e32 v14, 0
	v_mov_b32_e32 v15, 0
	v_mov_b32_e32 v16, 0
	v_mov_b32_e32 v17, 0
	s_and_saveexec_b64 s[10:11], vcc
	s_cbranch_execz .LBB0_107
	v_or_b32_e32 v12, s27, v1
	v_mad_i64_i32 v[10:11], s[28:29], v12, s9, 0
	s_ashr_i32 s23, s22, 31
	v_lshl_add_u64 v[10:11], v[10:11], 2, s[20:21]
	s_lshl_b64 s[22:23], s[22:23], 2
	v_lshl_add_u64 v[10:11], v[10:11], 0, s[22:23]
	v_lshl_add_u64 v[26:27], v[10:11], 0, v[20:21]
	v_add_u32_e32 v10, 32, v12
	v_mad_i64_i32 v[10:11], s[28:29], v10, s9, 0
	v_lshl_add_u64 v[10:11], v[10:11], 2, s[20:21]
	v_lshl_add_u64 v[10:11], v[10:11], 0, s[22:23]
	v_lshl_add_u64 v[28:29], v[10:11], 0, v[20:21]
	global_load_dwordx4 v[10:13], v[26:27], off
	global_load_dwordx4 v[14:17], v[28:29], off
	v_lshl_add_u64 v[26:27], v[26:27], 0, v[252:253]
	v_lshl_add_u64 v[28:29], v[28:29], 0, v[252:253]
	global_load_dword v254, v[26:27], off
	global_load_dword v255, v[28:29], off
	s_branch .LBB0_107

.Ltsb_skip_1:
	s_mov_b32 s98, 1
	v_add_u32_e32 v10, s20, v18
	v_add_u32_e32 v252, 64, v10
	v_cmp_gt_i32_e32 vcc, s9, v252
	v_cndmask_b32_e64 v252, 0, 1, vcc
	v_lshlrev_b32_e32 v252, 8, v252
	v_mov_b32_e32 v253, 0
	s_lshl_b32 s25, s10, 6
	v_cmp_gt_i32_e32 vcc, s9, v10
	v_mov_b32_e32 v10, 0
	v_mov_b32_e32 v11, 0
	v_mov_b32_e32 v12, 0
	v_mov_b32_e32 v13, 0
	v_mov_b32_e32 v14, 0
	v_mov_b32_e32 v15, 0
	v_mov_b32_e32 v16, 0
	v_mov_b32_e32 v17, 0
	s_and_saveexec_b64 s[10:11], vcc
	s_cbranch_execz .LBB0_874
	v_or_b32_e32 v12, s25, v19
	v_mad_i64_i32 v[10:11], s[26:27], v12, s9, 0
	s_ashr_i32 s21, s20, 31
	v_lshl_add_u64 v[10:11], v[10:11], 2, s[18:19]
	s_lshl_b64 s[20:21], s[20:21], 2
	v_lshl_add_u64 v[10:11], v[10:11], 0, s[20:21]
	v_lshl_add_u64 v[26:27], v[10:11], 0, v[20:21]
	v_add_u32_e32 v10, 32, v12
	v_mad_i64_i32 v[10:11], s[26:27], v10, s9, 0
	v_lshl_add_u64 v[10:11], v[10:11], 2, s[18:19]
	v_lshl_add_u64 v[10:11], v[10:11], 0, s[20:21]
	v_lshl_add_u64 v[28:29], v[10:11], 0, v[20:21]
	global_load_dwordx4 v[10:13], v[26:27], off
	global_load_dwordx4 v[14:17], v[28:29], off
	v_lshl_add_u64 v[26:27], v[26:27], 0, v[252:253]
	v_lshl_add_u64 v[28:29], v[28:29], 0, v[252:253]
	global_load_dword v254, v[26:27], off
	global_load_dword v255, v[28:29], off
	s_branch .LBB0_874

.Ltsb_skip_4:
	s_mov_b32 s98, 1
	v_add_u32_e32 v10, s22, v18
	v_add_u32_e32 v252, 64, v10
	v_cmp_gt_i32_e32 vcc, s13, v252
	v_cndmask_b32_e64 v252, 0, 1, vcc
	v_lshlrev_b32_e32 v252, 8, v252
	v_mov_b32_e32 v253, 0
	s_lshl_b32 s26, s11, 6
	v_cmp_gt_i32_e32 vcc, s13, v10
	v_mov_b32_e32 v10, 0
	v_mov_b32_e32 v11, 0
	v_mov_b32_e32 v12, 0
	v_mov_b32_e32 v13, 0
	v_mov_b32_e32 v14, 0
	v_mov_b32_e32 v15, 0
	v_mov_b32_e32 v16, 0
	v_mov_b32_e32 v17, 0
	s_and_saveexec_b64 s[14:15], vcc
	s_cbranch_execz .LBB0_2288
	v_or_b32_e32 v12, s26, v19
	v_mad_i64_i32 v[10:11], s[28:29], v12, s13, 0
	s_ashr_i32 s23, s22, 31
	v_lshl_add_u64 v[10:11], v[10:11], 2, s[20:21]
	s_lshl_b64 s[22:23], s[22:23], 2
	v_lshl_add_u64 v[10:11], v[10:11], 0, s[22:23]
	v_lshl_add_u64 v[26:27], v[10:11], 0, v[20:21]
	v_add_u32_e32 v10, 32, v12
	v_mad_i64_i32 v[10:11], s[28:29], v10, s13, 0
	v_lshl_add_u64 v[10:11], v[10:11], 2, s[20:21]
	v_lshl_add_u64 v[10:11], v[10:11], 0, s[22:23]
	v_lshl_add_u64 v[28:29], v[10:11], 0, v[20:21]
	global_load_dwordx4 v[10:13], v[26:27], off
	global_load_dwordx4 v[14:17], v[28:29], off
	v_lshl_add_u64 v[26:27], v[26:27], 0, v[252:253]
	v_lshl_add_u64 v[28:29], v[28:29], 0, v[252:253]
	global_load_dword v254, v[26:27], off
	global_load_dword v255, v[28:29], off
	s_branch .LBB0_2288
